# attention tile loop: one static s_setprio 1 for waves 4-7 (younger half), reset after the loop
# speedup vs baseline: 1.0086x; 1.0022x over previous
; #define LAS __attribute__((address_space(3)))
; __device__ __forceinline__ void attn_block(LAS unsigned char* lds, const Ptrs& P, int b, int h, int qb, float negMb, float lam, int tid, int wid, int lane) {
;     const int comp = wid & 1, quarter = wid >> 1, l31 = lane & 31, hh = lane >> 5;
;     const int NT = 2 * qb + 2;
;     const size_t tok0 = (size_t)b * SEQ;
;     const int qpos = qb * 128 + quarter * 32 + l31;
;     bf16x8 qf[8];
;     { const bf16* qp = P.Q + (tok0 + qpos) * 1024 + h * 256 + comp * 128 + hh * 8;
; #pragma unroll
;       for (int ks = 0; ks < 8; ++ks) qf[ks] = *(const bf16x8*)(qp + ks * 16); }
;     const unsigned ldsw = (unsigned)wid * 4096u;
;     const unsigned lds0 = (unsigned)__builtin_amdgcn_readfirstlane((int)(unsigned)(uintptr_t)lds);
;     unsigned kb0, kx16, vb0, vy16;
;     { int ln_ = lane; asm volatile("" : "+v"(ln_));
;       kb0 = (unsigned)(((16 * (wid & 3) + (ln_ >> 4)) * 1024 + h * 256 + (wid >> 2) * 128) * 2); kx16 = (unsigned)(((ln_ & 15) ^ (ln_ >> 4)) << 4);
;       vb0 = (unsigned)(((h * 256 + 32 * wid + (ln_ >> 3)) * M_TOK) * 2); vy16 = (unsigned)(((ln_ & 7) ^ (ln_ >> 4)) << 4);
;       asm volatile("" : "+v"(kb0), "+v"(kx16), "+v"(vb0), "+v"(vy16)); }
;     ...
;     f32x16 o[8];
; #pragma unroll
;     for (int e = 0; e < 8; ++e)
; #pragma unroll
;         for (int r = 0; r < 16; ++r) o[e][r] = 0.f;
;     float lsum = 0.f;
.LBB0_413:
	s_xor_b64 s[40:41], s[0:1], -1
	s_and_b64 s[0:1], s[0:1], exec
	s_cselect_b32 s2, s78, s77
	s_lshl_b32 s80, s2, 7
	s_add_i32 s80, s80, s50
	v_or_b32_e32 v194, s80, v203
	v_lshl_add_u64 v[18:19], s[20:21], 0, v[194:195]
	v_lshlrev_b64 v[18:19], 11, v[18:19]
	v_lshl_add_u64 v[18:19], v[198:199], 0, v[18:19]
	flat_load_dwordx4 v[190:193], v[18:19]
	flat_load_dwordx4 v[186:189], v[18:19] offset:32
	flat_load_dwordx4 v[182:185], v[18:19] offset:64
	flat_load_dwordx4 v[178:181], v[18:19] offset:96
	flat_load_dwordx4 v[174:177], v[18:19] offset:128
	flat_load_dwordx4 v[166:169], v[18:19] offset:160
	flat_load_dwordx4 v[170:173], v[18:19] offset:192
	flat_load_dwordx4 v[162:165], v[18:19] offset:224
	v_mov_b32_e32 v51, v1
	s_lshl_b32 s82, s2, 17
	v_ashrrev_i32_e32 v52, 4, v51
	v_lshrrev_b32_e32 v53, 3, v51
	v_add_u32_e32 v54, s51, v52
	v_bitop3_b32 v55, v51, v52, 15 bitop3:0x6c
	v_bitop3_b32 v51, v51, v52, 7 bitop3:0x6c
	v_add_lshl_u32 v53, s79, v53, 16
	v_lshl_add_u32 v52, v54, 11, s4
	v_lshlrev_b32_e32 v54, 4, v55
	v_lshlrev_b32_e32 v51, 4, v51
	s_waitcnt vmcnt(0)
	v_mov_b32_e32 v194, 0
	v_add_u32_e32 v206, v52, v54
	v_xor_b32_e32 v55, 64, v54
	v_xor_b32_e32 v56, 0x80, v54
	v_add3_u32 v208, v52, v55, s71
	v_xor_b32_e32 v54, 0xc0, v54
	v_add3_u32 v209, v52, v56, s72
	v_add3_u32 v210, v52, v54, s73
	v_add_u32_e32 v207, v53, v51
	v_xad_u32 v51, v51, 64, v53
	v_add_u32_e32 v211, 0x80000, v51
	v_add_u32_e32 v212, 0x100000, v207
	v_add_u32_e32 v213, 0x180000, v51
	s_mov_b32 s81, 0
	s_mov_b64 s[0:1], s[38:39]
	s_mov_b64 s[42:43], s[36:37]
	v_mov_b32_e32 v18, 0
	v_mov_b32_e32 v34, 0
	v_mov_b32_e32 v50, 0
	v_mov_b32_e32 v19, v194
	v_mov_b32_e32 v20, v194
	v_mov_b32_e32 v21, v194
	v_mov_b32_e32 v22, v194
	v_mov_b32_e32 v23, v194
	v_mov_b32_e32 v24, v194
	v_mov_b32_e32 v25, v194
	v_mov_b32_e32 v26, v194
	v_mov_b32_e32 v27, v194
	v_mov_b32_e32 v28, v194
	v_mov_b32_e32 v29, v194
	v_mov_b32_e32 v30, v194
	v_mov_b32_e32 v31, v194
	v_mov_b32_e32 v32, v194
	v_mov_b32_e32 v33, v194
	v_mov_b32_e32 v35, v194
	v_mov_b32_e32 v36, v194
	v_mov_b32_e32 v37, v194
	v_mov_b32_e32 v38, v194
	v_mov_b32_e32 v39, v194
	v_mov_b32_e32 v40, v194
	v_mov_b32_e32 v41, v194
	v_mov_b32_e32 v42, v194
	v_mov_b32_e32 v43, v194
	v_mov_b32_e32 v44, v194
	v_mov_b32_e32 v45, v194
	v_mov_b32_e32 v46, v194
	v_mov_b32_e32 v47, v194
	v_mov_b32_e32 v48, v194
	v_mov_b32_e32 v49, v194
	s_bitset1_b32 s82, 16
	v_mov_b32_e32 v51, v194
	v_mov_b32_e32 v52, v194
	v_mov_b32_e32 v53, v194
	v_mov_b32_e32 v54, v194
	v_mov_b32_e32 v55, v194
	v_mov_b32_e32 v56, v194
	v_mov_b32_e32 v57, v194
	v_mov_b32_e32 v58, v194
	s_waitcnt vmcnt(0) lgkmcnt(0)
; #define LAS __attribute__((address_space(3)))
; #define LDS_WAIT() asm volatile("s_waitcnt lgkmcnt(0)" ::: "memory")
; __device__ __forceinline__ int pi32(int i) { return (i & ~12) | ((i & 4) << 1) | ((i & 8) >> 1); }
; #define ATT_WAIT_V(n) asm volatile("s_waitcnt vmcnt(" #n ")" ::: "memory")
; #define ATT_BAR() do { asm volatile("" ::: "memory"); __builtin_amdgcn_s_barrier(); asm volatile("" ::: "memory"); } while (0)
; __device__ __forceinline__ void attn_block(LAS unsigned char* lds, const Ptrs& P, int b, int h, int qb, float negMb, float lam, int tid, int wid, int lane) {
;     ...
;     f32x16 o[8];
; #pragma unroll
;     for (int e = 0; e < 8; ++e)
; #pragma unroll
;         for (int r = 0; r < 16; ++r) o[e][r] = 0.f;
;     float lsum = 0.f;
;     ATT_WAIT_V(0);
; #pragma unroll
;     for (int ks = 0; ks < 8; ++ks) asm volatile("" : "+v"(qf[ks]));
;     ATT_DMA(0, 0);
;     const bool early = wid < 4;
;     for (int t = 0; t < NT; ++t) {
;         ATT_WAIT_V(0);
;         LDS_WAIT();
;         ATT_BAR();
;         const bool more = t + 1 < NT;
;         if (more && early) ATT_DMA(t + 1, (t + 1) & 1);
;         const bool active = (quarter >= 2) || more;
;         const LAS unsigned char* base = lds + (t & 1) * BUF;
;         int ln2 = lane; asm volatile("" : "+v"(ln2));
;         const int l31b = ln2 & 31, hhb = ln2 >> 5;
;         const int krow = pi32(l31b), kx = krow & 15;
;         const int koffr = comp * 16384 + krow * 256;
;         const int vx = (l31b >> 1) & 7;
;         const int voffr = V_OFF + l31b * 128;
	s_mov_b32 s2, m0
	s_mov_b32 m0, s54
	s_nop 0
	global_load_lds_dwordx4 v206, s[24:25]
	s_mov_b32 m0, s2
	v_mov_b32_e32 v59, v194
	s_mov_b32 s2, m0
	s_mov_b32 m0, s55
	s_nop 0
	global_load_lds_dwordx4 v208, s[24:25]
	s_mov_b32 m0, s2
	v_mov_b32_e32 v60, v194
	s_mov_b32 s2, m0
	s_mov_b32 m0, s56
	s_nop 0
	global_load_lds_dwordx4 v209, s[24:25]
	s_mov_b32 m0, s2
	v_mov_b32_e32 v61, v194
	s_mov_b32 s2, m0
	s_mov_b32 m0, s57
	s_nop 0
	global_load_lds_dwordx4 v210, s[24:25]
	s_mov_b32 m0, s2
	v_mov_b32_e32 v62, v194
	s_mov_b32 s2, m0
	s_mov_b32 m0, s61
	s_nop 0
	global_load_lds_dwordx4 v207, s[26:27]
	s_mov_b32 m0, s2
	v_mov_b32_e32 v63, v194
	s_mov_b32 s2, m0
	s_mov_b32 m0, s62
	s_nop 0
	global_load_lds_dwordx4 v211, s[26:27]
	s_mov_b32 m0, s2
	v_mov_b32_e32 v64, v194
	s_mov_b32 s2, m0
	s_mov_b32 m0, s63
	s_nop 0
	global_load_lds_dwordx4 v212, s[26:27]
	s_mov_b32 m0, s2
	v_mov_b32_e32 v65, v194
	s_mov_b32 s2, m0
	s_mov_b32 m0, s64
	s_nop 0
	global_load_lds_dwordx4 v213, s[26:27]
	s_mov_b32 m0, s2
	v_mov_b32_e32 v66, 0
	v_mov_b32_e32 v67, v194
	v_mov_b32_e32 v68, v194
	v_mov_b32_e32 v69, v194
	v_mov_b32_e32 v70, v194
	v_mov_b32_e32 v71, v194
	v_mov_b32_e32 v72, v194
	v_mov_b32_e32 v73, v194
	v_mov_b32_e32 v74, v194
	v_mov_b32_e32 v75, v194
	v_mov_b32_e32 v76, v194
	v_mov_b32_e32 v77, v194
	v_mov_b32_e32 v78, v194
	v_mov_b32_e32 v79, v194
	v_mov_b32_e32 v80, v194
	v_mov_b32_e32 v81, v194
	v_mov_b32_e32 v82, 0
	v_mov_b32_e32 v83, v194
	v_mov_b32_e32 v84, v194
	v_mov_b32_e32 v85, v194
	v_mov_b32_e32 v86, v194
	v_mov_b32_e32 v87, v194
	v_mov_b32_e32 v88, v194
	v_mov_b32_e32 v89, v194
	v_mov_b32_e32 v90, v194
	v_mov_b32_e32 v91, v194
	v_mov_b32_e32 v92, v194
	v_mov_b32_e32 v93, v194
	v_mov_b32_e32 v94, v194
	v_mov_b32_e32 v95, v194
	v_mov_b32_e32 v96, v194
	v_mov_b32_e32 v97, v194
	v_mov_b32_e32 v98, 0
	v_mov_b32_e32 v99, v194
	v_mov_b32_e32 v100, v194
	v_mov_b32_e32 v101, v194
	v_mov_b32_e32 v102, v194
	v_mov_b32_e32 v103, v194
	v_mov_b32_e32 v104, v194
	v_mov_b32_e32 v105, v194
	v_mov_b32_e32 v106, v194
	v_mov_b32_e32 v107, v194
	v_mov_b32_e32 v108, v194
	v_mov_b32_e32 v109, v194
	v_mov_b32_e32 v110, v194
	v_mov_b32_e32 v111, v194
	v_mov_b32_e32 v112, v194
	v_mov_b32_e32 v113, v194
	v_mov_b32_e32 v114, 0
	v_mov_b32_e32 v115, v194
	v_mov_b32_e32 v116, v194
	v_mov_b32_e32 v117, v194
	v_mov_b32_e32 v118, v194
	v_mov_b32_e32 v119, v194
	v_mov_b32_e32 v120, v194
	v_mov_b32_e32 v121, v194
	v_mov_b32_e32 v122, v194
	v_mov_b32_e32 v123, v194
	v_mov_b32_e32 v124, v194
	v_mov_b32_e32 v125, v194
	v_mov_b32_e32 v126, v194
	v_mov_b32_e32 v127, v194
	v_mov_b32_e32 v128, v194
	v_mov_b32_e32 v129, v194
	v_mov_b32_e32 v130, 0
	v_mov_b32_e32 v131, v194
	v_mov_b32_e32 v132, v194
	v_mov_b32_e32 v133, v194
	v_mov_b32_e32 v134, v194
	v_mov_b32_e32 v135, v194
	v_mov_b32_e32 v136, v194
	v_mov_b32_e32 v137, v194
	v_mov_b32_e32 v138, v194
	v_mov_b32_e32 v139, v194
	v_mov_b32_e32 v140, v194
	v_mov_b32_e32 v141, v194
	v_mov_b32_e32 v142, v194
	v_mov_b32_e32 v143, v194
	v_mov_b32_e32 v144, v194
	v_mov_b32_e32 v145, v194
	v_lshrrev_b32_e32 v226, 5, v1
	v_and_b32_e32 v227, 19, v1
	v_lshlrev_b32_e32 v228, 1, v1
	v_and_b32_e32 v228, 8, v228
	v_lshrrev_b32_e32 v229, 1, v1
	v_and_b32_e32 v230, 4, v229
	v_or3_b32 v227, v227, v228, v230
	v_and_b32_e32 v231, 15, v227
	v_lshl_add_u32 v232, v227, 8, s65
	v_xor_b32_e32 v233, v226, v231
	v_lshl_add_u32 v214, v233, 4, v232
	v_add_u32_e32 v233, 2, v226
	v_xor_b32_e32 v233, v233, v231
	v_lshl_add_u32 v215, v233, 4, v232
	v_add_u32_e32 v233, 4, v226
	v_xor_b32_e32 v233, v233, v231
	v_lshl_add_u32 v216, v233, 4, v232
	v_add_u32_e32 v233, 6, v226
	v_xor_b32_e32 v233, v233, v231
	v_lshl_add_u32 v217, v233, 4, v232
	v_add_u32_e32 v233, 8, v226
	v_xor_b32_e32 v233, v233, v231
	v_lshl_add_u32 v218, v233, 4, v232
	v_add_u32_e32 v233, 10, v226
	v_xor_b32_e32 v233, v233, v231
	v_lshl_add_u32 v219, v233, 4, v232
	v_add_u32_e32 v233, 12, v226
	v_xor_b32_e32 v233, v233, v231
	v_lshl_add_u32 v220, v233, 4, v232
	v_add_u32_e32 v233, 14, v226
	v_xor_b32_e32 v233, v233, v231
	v_lshl_add_u32 v221, v233, 4, v232
	v_and_b32_e32 v234, 7, v229
	v_and_b32_e32 v235, 31, v1
	v_lshlrev_b32_e32 v235, 7, v235
	v_xor_b32_e32 v233, v226, v234
	v_lshl_add_u32 v222, v233, 4, v235
	v_add_u32_e32 v233, 2, v226
	v_xor_b32_e32 v233, v233, v234
	v_lshl_add_u32 v223, v233, 4, v235
	v_add_u32_e32 v233, 4, v226
	v_xor_b32_e32 v233, v233, v234
	v_lshl_add_u32 v224, v233, 4, v235
	v_add_u32_e32 v233, 6, v226
	v_xor_b32_e32 v233, v233, v234
	v_lshl_add_u32 v225, v233, 4, v235
	v_mov_b32_e32 v254, 0
	v_mov_b32_e32 v255, 0
	s_and_b64 vcc, exec, s[12:13]
	s_cbranch_vccz .Lat_noprio
	s_setprio 1
.Lat_noprio:
	s_branch .Lat_tile

; #define LAS __attribute__((address_space(3)))
; __device__ __forceinline__ unsigned pk2(float lo, float hi) { return pg8::cvt_pk_bf16(lo, hi); }
; __device__ __forceinline__ void attn_block(LAS unsigned char* lds, const Ptrs& P, int b, int h, int qb, float negMb, float lam, int tid, int wid, int lane) {
;     ...
;                 float ps = 0.f;
; #pragma unroll
;                 for (int r = 0; r < 16; ++r) { s[r] = __builtin_amdgcn_exp2f(s[r]); ps += s[r]; }
;                 lsum += ps;
; #pragma unroll
;                 for (int sI = 0; sI < 2; ++sI) { v4u w;
; #pragma unroll
;                     for (int j = 0; j < 4; ++j) w[j] = pk2(s[8 * sI + 2 * j], s[8 * sI + 2 * j + 1]);
;                     const bf16x8 pf = __builtin_bit_cast(bf16x8, w);
;                     const LAS unsigned char* vb = base + voffr + (((2 * (2 * T + sI) + hhb) ^ vx) << 4);
; #pragma unroll
;                     for (int e = 0; e < 8; ++e) {
;                         const bf16x8 vf = *(const LAS bf16x8*)(vb + e * 4096);
;                         o[e] = __builtin_amdgcn_mfma_f32_32x32x16_bf16(vf, pf, o[e], 0, 0, 0);
;                     }
;                 }
;             }
;         }
;     }
.Lat_pv1:
	s_waitcnt lgkmcnt(2)
	v_mfma_f32_32x32x16_bf16 v[130:145], v[234:237], v[238:241], v[130:145]
	v_exp_f32_e32 v246, v246
	v_exp_f32_e32 v247, v247
	v_exp_f32_e32 v248, v248
	ds_read_b128 v[234:237], v224 offset:45056
	s_waitcnt lgkmcnt(2)
	v_mfma_f32_32x32x16_bf16 v[114:129], v[226:229], v[238:241], v[114:129]
	v_exp_f32_e32 v249, v249
	v_exp_f32_e32 v250, v250
	v_exp_f32_e32 v251, v251
	ds_read_b128 v[226:229], v224 offset:49152
	s_waitcnt lgkmcnt(2)
	v_mfma_f32_32x32x16_bf16 v[98:113], v[230:233], v[238:241], v[98:113]
	v_exp_f32_e32 v252, v252
	v_exp_f32_e32 v253, v253
	v_add_f32_e32 v254, v254, v246
	ds_read_b128 v[230:233], v224 offset:53248
	s_waitcnt lgkmcnt(2)
	v_mfma_f32_32x32x16_bf16 v[82:97], v[234:237], v[238:241], v[82:97]
	v_add_f32_e32 v255, v255, v247
	v_add_f32_e32 v254, v254, v248
	v_add_f32_e32 v255, v255, v249
	ds_read_b128 v[234:237], v224 offset:57344
	s_waitcnt lgkmcnt(2)
	v_mfma_f32_32x32x16_bf16 v[66:81], v[226:229], v[238:241], v[66:81]
	v_add_f32_e32 v254, v254, v250
	v_add_f32_e32 v255, v255, v251
	v_add_f32_e32 v254, v254, v252
	ds_read_b128 v[226:229], v224 offset:61440
	s_waitcnt lgkmcnt(2)
	v_mfma_f32_32x32x16_bf16 v[50:65], v[230:233], v[238:241], v[50:65]
	v_add_f32_e32 v255, v255, v253
	v_cvt_pk_bf16_f32 v246, v246, v247
	v_cvt_pk_bf16_f32 v247, v248, v249
	ds_read_b128 v[230:233], v225 offset:32768
	s_waitcnt lgkmcnt(2)
	v_mfma_f32_32x32x16_bf16 v[34:49], v[234:237], v[238:241], v[34:49]
	v_cvt_pk_bf16_f32 v248, v250, v251
	v_cvt_pk_bf16_f32 v249, v252, v253
	ds_read_b128 v[234:237], v225 offset:36864
	s_waitcnt lgkmcnt(2)
	v_mfma_f32_32x32x16_bf16 v[18:33], v[226:229], v[238:241], v[18:33]
	ds_read_b128 v[226:229], v225 offset:40960
	s_waitcnt lgkmcnt(2)
	v_mfma_f32_32x32x16_bf16 v[130:145], v[230:233], v[246:249], v[130:145]
	v_xor_b32_e32 v214, 0x10000, v214
	v_xor_b32_e32 v215, 0x10000, v215
	ds_read_b128 v[230:233], v225 offset:45056
	s_waitcnt lgkmcnt(2)
	v_mfma_f32_32x32x16_bf16 v[114:129], v[234:237], v[246:249], v[114:129]
	v_xor_b32_e32 v216, 0x10000, v216
	v_xor_b32_e32 v217, 0x10000, v217
	ds_read_b128 v[234:237], v225 offset:49152
	s_waitcnt lgkmcnt(2)
	v_mfma_f32_32x32x16_bf16 v[98:113], v[226:229], v[246:249], v[98:113]
	v_xor_b32_e32 v218, 0x10000, v218
	v_xor_b32_e32 v219, 0x10000, v219
	ds_read_b128 v[226:229], v225 offset:53248
	s_waitcnt lgkmcnt(2)
	v_mfma_f32_32x32x16_bf16 v[82:97], v[230:233], v[246:249], v[82:97]
	v_xor_b32_e32 v220, 0x10000, v220
	v_xor_b32_e32 v221, 0x10000, v221
	ds_read_b128 v[230:233], v225 offset:57344
	s_waitcnt lgkmcnt(2)
	v_mfma_f32_32x32x16_bf16 v[66:81], v[234:237], v[246:249], v[66:81]
	v_xor_b32_e32 v222, 0x10000, v222
	v_xor_b32_e32 v223, 0x10000, v223
	ds_read_b128 v[234:237], v225 offset:61440
	s_waitcnt lgkmcnt(2)
	v_mfma_f32_32x32x16_bf16 v[50:65], v[226:229], v[246:249], v[50:65]
	v_xor_b32_e32 v224, 0x10000, v224
	s_waitcnt lgkmcnt(1)
	v_mfma_f32_32x32x16_bf16 v[34:49], v[230:233], v[246:249], v[34:49]
	v_xor_b32_e32 v225, 0x10000, v225
	s_waitcnt lgkmcnt(0)
	v_mfma_f32_32x32x16_bf16 v[18:33], v[234:237], v[246:249], v[18:33]
	s_add_i32 s81, s81, 0x10000
	s_add_u32 s42, s42, 0x80
	s_addc_u32 s43, s43, 0
	s_add_u32 s0, s0, 0x20000
	s_addc_u32 s1, s1, 0
	s_cmp_eq_u32 s82, s81
	s_cbranch_scc0 .Lat_tile
	s_setprio 0
	s_not_b64 s[2:3], s[12:13]
	s_nop 0
	v_add_f32_e32 v194, v194, v254
	v_add_f32_e32 v194, v194, v255
